# quant_gu (P5): the 16 row loads are issued without waiting for the column-maxima load; reciprocal set-up moved behind the loads with vmcnt(16)
# speedup vs baseline: 1.0123x; 1.0123x over previous
.LBB0_1149:
	s_mul_hi_i32 s6, s46, 0x2fa0be83
	s_lshr_b32 s7, s6, 31
	s_ashr_i32 s6, s6, 7
	s_add_i32 s7, s6, s7
	s_mul_i32 s8, s7, 0xffffaa00
	s_lshl_b32 s6, s7, 7
	s_add_i32 s8, s3, s8
	s_mulk_i32 s7, 0xd500
	s_bitcmp0_b32 s46, 2
	v_add_u32_e32 v8, s8, v2
	s_cselect_b32 s10, s15, s17
	s_cselect_b32 s47, s14, s16
	s_add_i32 s11, s23, s7
	v_ashrrev_i32_e32 v9, 31, v8
	v_add_u32_e32 v10, s6, v0
	s_ashr_i32 s9, s8, 31
	v_mov_b32_e32 v12, s47
	v_mov_b32_e32 v13, s10
	s_and_b32 s10, s11, 0xffffff80
	v_lshlrev_b64 v[8:9], 12, v[8:9]
	s_and_b32 s20, s8, 0x60
	s_ashr_i32 s7, s6, 31
	v_lshl_add_u64 v[14:15], s[8:9], 2, v[6:7]
	v_mad_i64_i32 v[10:11], s[8:9], v10, s25, v[12:13]
	s_ashr_i32 s11, s10, 31
	v_lshl_add_u64 v[8:9], s[64:65], 0, v[8:9]
	s_lshl_b32 s20, s20, 2
	v_lshl_add_u64 v[10:11], s[10:11], 2, v[10:11]
	v_lshl_add_u64 v[8:9], v[8:9], 0, s[6:7]
	v_lshl_add_u64 v[16:17], v[10:11], 0, s[20:21]
	v_lshl_add_u64 v[10:11], v[8:9], 0, v[0:1]
	v_add_co_u32_e32 v8, vcc, s45, v10
	v_lshl_add_u64 v[16:17], v[16:17], 0, v[4:5]
	s_nop 0
	v_addc_co_u32_e32 v9, vcc, 0, v11, vcc
	v_add_co_u32_e32 v20, vcc, s26, v16
	global_load_dwordx4 v[12:15], v[14:15], off
	s_nop 0
	v_addc_co_u32_e32 v21, vcc, 0, v17, vcc
	v_add_co_u32_e32 v24, vcc, s27, v16
	s_add_i32 s46, s46, s94
	s_nop 0
	v_addc_co_u32_e32 v25, vcc, 0, v17, vcc
	v_add_co_u32_e32 v28, vcc, s28, v16
	s_add_i32 s3, s3, s22
	s_nop 0
	v_addc_co_u32_e32 v29, vcc, 0, v17, vcc
	v_add_co_u32_e32 v32, vcc, s29, v16
	s_add_i32 s23, s23, s24
	s_nop 0
	v_addc_co_u32_e32 v33, vcc, 0, v17, vcc
	v_add_co_u32_e32 v36, vcc, s30, v16
	s_cmpk_lt_i32 s46, 0x5600
	s_nop 0
	v_addc_co_u32_e32 v37, vcc, 0, v17, vcc
	v_add_co_u32_e32 v40, vcc, s31, v16
	s_nop 0
	s_nop 0
	v_addc_co_u32_e32 v41, vcc, 0, v17, vcc
	v_add_co_u32_e32 v44, vcc, s33, v16
	s_nop 0
	s_nop 0
	v_addc_co_u32_e32 v45, vcc, 0, v17, vcc
	v_add_co_u32_e32 v48, vcc, s34, v16
	s_nop 0
	s_nop 0
	v_addc_co_u32_e32 v49, vcc, 0, v17, vcc
	v_add_co_u32_e32 v52, vcc, s35, v16
	s_nop 0
	s_nop 0
	v_addc_co_u32_e32 v53, vcc, 0, v17, vcc
	v_add_co_u32_e32 v56, vcc, s36, v16
	s_nop 0
	s_nop 0
	v_addc_co_u32_e32 v57, vcc, 0, v17, vcc
	v_add_co_u32_e32 v60, vcc, s37, v16
	s_nop 0
	s_nop 0
	v_addc_co_u32_e32 v61, vcc, 0, v17, vcc
	v_add_co_u32_e32 v64, vcc, s38, v16
	s_nop 0
	s_nop 0
	v_addc_co_u32_e32 v65, vcc, 0, v17, vcc
	v_add_co_u32_e32 v68, vcc, s39, v16
	s_nop 0
	s_nop 0
	v_addc_co_u32_e32 v69, vcc, 0, v17, vcc
	v_add_co_u32_e32 v72, vcc, s40, v16
	s_nop 0
	s_nop 0
	v_addc_co_u32_e32 v73, vcc, 0, v17, vcc
	v_add_co_u32_e32 v76, vcc, s41, v16
	s_nop 0
	s_nop 0
	v_addc_co_u32_e32 v77, vcc, 0, v17, vcc
	global_load_dwordx4 v[16:19], v[16:17], off nt
	s_nop 0
	global_load_dwordx4 v[20:23], v[20:21], off offset:3072 nt
	s_nop 0
	global_load_dwordx4 v[24:27], v[24:25], off offset:2048 nt
	s_nop 0
	global_load_dwordx4 v[28:31], v[28:29], off offset:1024 nt
	s_nop 0
	global_load_dwordx4 v[32:35], v[32:33], off nt
	s_nop 0
	global_load_dwordx4 v[36:39], v[36:37], off offset:3072 nt
	s_nop 0
	global_load_dwordx4 v[40:43], v[40:41], off offset:2048 nt
	s_nop 0
	global_load_dwordx4 v[44:47], v[44:45], off offset:1024 nt
	s_nop 0
	global_load_dwordx4 v[48:51], v[48:49], off nt
	s_nop 0
	global_load_dwordx4 v[52:55], v[52:53], off offset:3072 nt
	s_nop 0
	global_load_dwordx4 v[56:59], v[56:57], off offset:2048 nt
	s_nop 0
	global_load_dwordx4 v[60:63], v[60:61], off offset:1024 nt
	s_nop 0
	global_load_dwordx4 v[64:67], v[64:65], off nt
	s_nop 0
	global_load_dwordx4 v[68:71], v[68:69], off offset:3072 nt
	s_nop 0
	global_load_dwordx4 v[72:75], v[72:73], off offset:2048 nt
	s_nop 0
	global_load_dwordx4 v[76:79], v[76:77], off offset:1024 nt
	s_waitcnt vmcnt(16)
	v_div_scale_f32 v80, s[6:7], v12, v12, s42
	v_div_scale_f32 v82, s[6:7], v13, v13, s42
	v_rcp_f32_e32 v88, v80
	v_rcp_f32_e32 v89, v82
	v_div_scale_f32 v84, s[8:9], v14, v14, s42
	v_rcp_f32_e32 v90, v84
	v_div_scale_f32 v86, s[10:11], v15, v15, s42
	v_fma_f32 v92, -v80, v88, 1.0
	v_rcp_f32_e32 v91, v86
	v_fma_f32 v93, -v82, v89, 1.0
	v_div_scale_f32 v81, vcc, s42, v12, s42
	v_fmac_f32_e32 v88, v92, v88
	v_div_scale_f32 v83, s[6:7], s42, v13, s42
	v_fmac_f32_e32 v89, v93, v89
	v_mul_f32_e32 v92, v81, v88
	v_fma_f32 v94, -v84, v90, 1.0
	v_mul_f32_e32 v93, v83, v89
	v_fma_f32 v96, -v80, v92, v81
	v_div_scale_f32 v85, s[8:9], s42, v14, s42
	v_fmac_f32_e32 v90, v94, v90
	v_fma_f32 v97, -v82, v93, v83
	v_fmac_f32_e32 v92, v96, v88
	v_fma_f32 v95, -v86, v91, 1.0
	v_mul_f32_e32 v94, v85, v90
	v_fmac_f32_e32 v93, v97, v89
	v_fma_f32 v80, -v80, v92, v81
	v_div_scale_f32 v87, s[10:11], s42, v15, s42
	v_fmac_f32_e32 v91, v95, v91
	v_fma_f32 v98, -v84, v94, v85
	v_fma_f32 v81, -v82, v93, v83
	v_div_fmas_f32 v80, v80, v88, v92
	s_mov_b64 vcc, s[6:7]
	v_mul_f32_e32 v95, v87, v91
	v_fmac_f32_e32 v94, v98, v90
	v_div_fixup_f32 v80, v80, v12, s42
	v_div_fmas_f32 v81, v81, v89, v93
	v_cmp_lt_f32_e32 vcc, 0, v12
	v_fma_f32 v99, -v86, v95, v87
	v_fma_f32 v82, -v84, v94, v85
	v_cndmask_b32_e32 v12, 0, v80, vcc
	s_mov_b64 vcc, s[8:9]
	v_fmac_f32_e32 v95, v99, v91
	v_div_fixup_f32 v80, v81, v13, s42
	v_div_fmas_f32 v81, v82, v90, v94
	v_cmp_lt_f32_e32 vcc, 0, v13
	v_fma_f32 v83, -v86, v95, v87
	v_cmp_lt_f32_e64 s[6:7], 0, v14
	v_cndmask_b32_e32 v13, 0, v80, vcc
	s_mov_b64 vcc, s[10:11]
	v_div_fixup_f32 v80, v81, v14, s42
	v_div_fmas_f32 v81, v83, v91, v95
	v_cndmask_b32_e64 v14, 0, v80, s[6:7]
	v_div_fixup_f32 v80, v81, v15, s42
	s_waitcnt vmcnt(15)
	v_mul_f32_e32 v16, v16, v12
	s_waitcnt vmcnt(14)
	v_mul_f32_e32 v20, v20, v12
	s_waitcnt vmcnt(13)
	v_mul_f32_e32 v24, v24, v12
	s_waitcnt vmcnt(12)
	v_mul_f32_e32 v28, v28, v12
	s_waitcnt vmcnt(11)
	v_mul_f32_e32 v32, v32, v12
	s_waitcnt vmcnt(10)
	v_mul_f32_e32 v36, v36, v12
	s_waitcnt vmcnt(9)
	v_mul_f32_e32 v40, v40, v12
	s_waitcnt vmcnt(8)
	v_mul_f32_e32 v44, v44, v12
	s_waitcnt vmcnt(7)
	v_mul_f32_e32 v48, v48, v12
	s_waitcnt vmcnt(6)
	v_mul_f32_e32 v52, v52, v12
	s_waitcnt vmcnt(5)
	v_mul_f32_e32 v56, v56, v12
	s_waitcnt vmcnt(4)
	v_mul_f32_e32 v60, v60, v12
	s_waitcnt vmcnt(3)
	v_mul_f32_e32 v64, v64, v12
	s_waitcnt vmcnt(2)
	v_mul_f32_e32 v68, v68, v12
	s_waitcnt vmcnt(1)
	v_mul_f32_e32 v72, v72, v12
	s_waitcnt vmcnt(0)
	v_mul_f32_e32 v76, v76, v12
	v_add_co_u32_e32 v12, vcc, 0x3000, v10
	v_mul_f32_e32 v17, v17, v13
	v_mul_f32_e32 v21, v21, v13
	v_mul_f32_e32 v25, v25, v13
	v_mul_f32_e32 v29, v29, v13
	v_mul_f32_e32 v33, v33, v13
	v_mul_f32_e32 v37, v37, v13
	v_mul_f32_e32 v41, v41, v13
	v_mul_f32_e32 v45, v45, v13
	v_mul_f32_e32 v49, v49, v13
	v_mul_f32_e32 v53, v53, v13
	v_mul_f32_e32 v57, v57, v13
	v_mul_f32_e32 v61, v61, v13
	v_mul_f32_e32 v65, v65, v13
	v_mul_f32_e32 v69, v69, v13
	v_mul_f32_e32 v73, v73, v13
	v_mul_f32_e32 v77, v77, v13
	v_addc_co_u32_e32 v13, vcc, 0, v11, vcc
	v_rndne_f32_e32 v16, v16
	v_rndne_f32_e32 v20, v20
	v_rndne_f32_e32 v24, v24
	v_rndne_f32_e32 v28, v28
	v_rndne_f32_e32 v32, v32
	v_rndne_f32_e32 v36, v36
	v_rndne_f32_e32 v40, v40
	v_rndne_f32_e32 v44, v44
	v_rndne_f32_e32 v48, v48
	v_rndne_f32_e32 v52, v52
	v_rndne_f32_e32 v56, v56
	v_rndne_f32_e32 v60, v60
	v_rndne_f32_e32 v64, v64
	v_rndne_f32_e32 v68, v68
	v_rndne_f32_e32 v72, v72
	v_rndne_f32_e32 v76, v76
	v_cmp_lt_f32_e32 vcc, 0, v15
	v_cvt_i32_f32_e32 v16, v16
	v_cvt_i32_f32_e32 v20, v20
	v_cndmask_b32_e32 v15, 0, v80, vcc
	v_cvt_i32_f32_e32 v24, v24
	v_cvt_i32_f32_e32 v28, v28
	v_cvt_i32_f32_e32 v32, v32
	v_cvt_i32_f32_e32 v36, v36
	v_cvt_i32_f32_e32 v40, v40
	v_cvt_i32_f32_e32 v44, v44
	v_cvt_i32_f32_e32 v48, v48
	v_cvt_i32_f32_e32 v52, v52
	v_cvt_i32_f32_e32 v56, v56
	v_cvt_i32_f32_e32 v60, v60
	v_cvt_i32_f32_e32 v64, v64
	v_cvt_i32_f32_e32 v68, v68
	v_cvt_i32_f32_e32 v72, v72
	v_cvt_i32_f32_e32 v76, v76
	v_rndne_f32_e32 v21, v21
	v_rndne_f32_e32 v25, v25
	v_rndne_f32_e32 v33, v33
	v_rndne_f32_e32 v37, v37
	v_rndne_f32_e32 v41, v41
	v_rndne_f32_e32 v45, v45
	v_rndne_f32_e32 v49, v49
	v_rndne_f32_e32 v53, v53
	v_rndne_f32_e32 v57, v57
	v_rndne_f32_e32 v61, v61
	v_rndne_f32_e32 v65, v65
	v_rndne_f32_e32 v69, v69
	v_rndne_f32_e32 v73, v73
	v_mul_f32_e32 v18, v18, v14
	v_mul_f32_e32 v22, v22, v14
	v_mul_f32_e32 v26, v26, v14
	v_mul_f32_e32 v30, v30, v14
	v_mul_f32_e32 v38, v38, v14
	v_mul_f32_e32 v42, v42, v14
	v_mul_f32_e32 v50, v50, v14
	v_mul_f32_e32 v54, v54, v14
	v_mul_f32_e32 v58, v58, v14
	v_mul_f32_e32 v62, v62, v14
	v_mul_f32_e32 v66, v66, v14
	v_mul_f32_e32 v70, v70, v14
	v_mul_f32_e32 v74, v74, v14
	v_rndne_f32_e32 v17, v17
	v_rndne_f32_e32 v29, v29
	v_rndne_f32_e32 v77, v77
	v_mul_f32_e32 v34, v34, v14
	v_mul_f32_e32 v46, v46, v14
	v_mul_f32_e32 v14, v78, v14
	v_cvt_i32_f32_e32 v21, v21
	v_cvt_i32_f32_e32 v25, v25
	v_cvt_i32_f32_e32 v33, v33
	v_cvt_i32_f32_e32 v37, v37
	v_cvt_i32_f32_e32 v41, v41
	v_cvt_i32_f32_e32 v45, v45
	v_cvt_i32_f32_e32 v49, v49
	v_cvt_i32_f32_e32 v53, v53
	v_cvt_i32_f32_e32 v57, v57
	v_cvt_i32_f32_e32 v61, v61
	v_cvt_i32_f32_e32 v65, v65
	v_cvt_i32_f32_e32 v69, v69
	v_cvt_i32_f32_e32 v73, v73
	v_rndne_f32_e32 v18, v18
	v_rndne_f32_e32 v22, v22
	v_rndne_f32_e32 v26, v26
	v_rndne_f32_e32 v30, v30
	v_rndne_f32_e32 v38, v38
	v_rndne_f32_e32 v42, v42
	v_rndne_f32_e32 v50, v50
	v_rndne_f32_e32 v54, v54
	v_rndne_f32_e32 v58, v58
	v_rndne_f32_e32 v62, v62
	v_rndne_f32_e32 v66, v66
	v_rndne_f32_e32 v70, v70
	v_rndne_f32_e32 v74, v74
	v_mul_f32_e32 v19, v19, v15
	v_mul_f32_e32 v23, v23, v15
	v_mul_f32_e32 v27, v27, v15
	v_mul_f32_e32 v31, v31, v15
	v_mul_f32_e32 v35, v35, v15
	v_mul_f32_e32 v39, v39, v15
	v_mul_f32_e32 v43, v43, v15
	v_mul_f32_e32 v47, v47, v15
	v_mul_f32_e32 v51, v51, v15
	v_mul_f32_e32 v55, v55, v15
	v_mul_f32_e32 v59, v59, v15
	v_mul_f32_e32 v71, v71, v15
	v_mul_f32_e32 v75, v75, v15
	v_cvt_i32_f32_e32 v17, v17
	v_cvt_i32_f32_e32 v29, v29
	v_cvt_i32_f32_e32 v77, v77
	v_rndne_f32_e32 v34, v34
	v_rndne_f32_e32 v46, v46
	v_rndne_f32_e32 v14, v14
	v_mul_f32_e32 v63, v63, v15
	v_mul_f32_e32 v67, v67, v15
	v_mul_f32_e32 v15, v79, v15
	v_cvt_i32_f32_e32 v18, v18
	v_cvt_i32_f32_e32 v22, v22
	v_cvt_i32_f32_e32 v26, v26
	v_cvt_i32_f32_e32 v30, v30
	v_cvt_i32_f32_e32 v38, v38
	v_cvt_i32_f32_e32 v42, v42
	v_cvt_i32_f32_e32 v50, v50
	v_cvt_i32_f32_e32 v54, v54
	v_cvt_i32_f32_e32 v58, v58
	v_cvt_i32_f32_e32 v62, v62
	v_cvt_i32_f32_e32 v66, v66
	v_cvt_i32_f32_e32 v70, v70
	v_cvt_i32_f32_e32 v74, v74
	v_rndne_f32_e32 v19, v19
	v_rndne_f32_e32 v23, v23
	v_rndne_f32_e32 v27, v27
	v_rndne_f32_e32 v31, v31
	v_rndne_f32_e32 v35, v35
	v_rndne_f32_e32 v39, v39
	v_rndne_f32_e32 v43, v43
	v_rndne_f32_e32 v47, v47
	v_rndne_f32_e32 v51, v51
	v_rndne_f32_e32 v55, v55
	v_rndne_f32_e32 v59, v59
	v_rndne_f32_e32 v71, v71
	v_rndne_f32_e32 v75, v75
	v_cvt_i32_f32_e32 v34, v34
	v_cvt_i32_f32_e32 v46, v46
	v_cvt_i32_f32_e32 v14, v14
	v_rndne_f32_e32 v63, v63
	v_rndne_f32_e32 v67, v67
	v_rndne_f32_e32 v15, v15
	v_cvt_i32_f32_e32 v19, v19
	v_cvt_i32_f32_e32 v23, v23
	v_cvt_i32_f32_e32 v27, v27
	v_cvt_i32_f32_e32 v31, v31
	v_cvt_i32_f32_e32 v35, v35
	v_cvt_i32_f32_e32 v39, v39
	v_cvt_i32_f32_e32 v43, v43
	v_cvt_i32_f32_e32 v47, v47
	v_cvt_i32_f32_e32 v51, v51
	v_cvt_i32_f32_e32 v55, v55
	v_cvt_i32_f32_e32 v59, v59
	v_cvt_i32_f32_e32 v71, v71
	v_cvt_i32_f32_e32 v75, v75
	v_cvt_i32_f32_e32 v63, v63
	v_cvt_i32_f32_e32 v67, v67
	v_cvt_i32_f32_e32 v78, v15
	v_med3_i32 v15, v16, s43, v3
	v_med3_i32 v16, v20, s43, v3
	v_med3_i32 v20, v24, s43, v3
	v_med3_i32 v24, v28, s43, v3
	v_med3_i32 v28, v32, s43, v3
	v_med3_i32 v32, v36, s43, v3
	v_med3_i32 v36, v40, s43, v3
	v_med3_i32 v40, v44, s43, v3
	v_med3_i32 v44, v48, s43, v3
	v_med3_i32 v48, v52, s43, v3
	v_med3_i32 v52, v56, s43, v3
	v_med3_i32 v56, v60, s43, v3
	v_med3_i32 v60, v64, s43, v3
	v_med3_i32 v64, v68, s43, v3
	v_med3_i32 v68, v72, s43, v3
	v_med3_i32 v72, v76, s43, v3
	v_lshlrev_b32_e32 v16, 8, v16
	v_lshlrev_b32_e32 v20, 16, v20
	v_perm_b32 v15, v24, v15, s44
	v_lshlrev_b32_e32 v24, 8, v32
	v_lshlrev_b32_e32 v32, 16, v36
	v_perm_b32 v28, v40, v28, s44
	v_lshlrev_b32_e32 v36, 8, v48
	v_lshlrev_b32_e32 v40, 16, v52
	v_perm_b32 v44, v56, v44, s44
	v_lshlrev_b32_e32 v48, 8, v64
	v_lshlrev_b32_e32 v52, 16, v68
	v_perm_b32 v56, v72, v60, s44
	v_med3_i32 v21, v21, s43, v3
	v_med3_i32 v25, v25, s43, v3
	v_med3_i32 v33, v33, s43, v3
	v_med3_i32 v37, v37, s43, v3
	v_med3_i32 v41, v41, s43, v3
	v_med3_i32 v45, v45, s43, v3
	v_med3_i32 v49, v49, s43, v3
	v_med3_i32 v53, v53, s43, v3
	v_med3_i32 v57, v57, s43, v3
	v_med3_i32 v60, v61, s43, v3
	v_med3_i32 v61, v65, s43, v3
	v_med3_i32 v64, v69, s43, v3
	v_med3_i32 v65, v73, s43, v3
	v_med3_i32 v17, v17, s43, v3
	v_med3_i32 v29, v29, s43, v3
	v_med3_i32 v68, v77, s43, v3
	v_and_b32_e32 v16, 0xff00, v16
	v_and_b32_e32 v20, 0xff0000, v20
	v_and_b32_e32 v24, 0xff00, v24
	v_and_b32_e32 v32, 0xff0000, v32
	v_and_b32_e32 v36, 0xff00, v36
	v_and_b32_e32 v40, 0xff0000, v40
	v_and_b32_e32 v48, 0xff00, v48
	v_and_b32_e32 v52, 0xff0000, v52
	v_lshlrev_b32_e32 v21, 8, v21
	v_lshlrev_b32_e32 v25, 16, v25
	v_lshlrev_b32_e32 v37, 8, v37
	v_lshlrev_b32_e32 v41, 16, v41
	v_perm_b32 v33, v45, v33, s44
	v_lshlrev_b32_e32 v45, 8, v53
	v_lshlrev_b32_e32 v53, 16, v57
	v_perm_b32 v49, v60, v49, s44
	v_lshlrev_b32_e32 v57, 8, v64
	v_lshlrev_b32_e32 v60, 16, v65
	v_med3_i32 v18, v18, s43, v3
	v_med3_i32 v22, v22, s43, v3
	v_med3_i32 v26, v26, s43, v3
	v_med3_i32 v30, v30, s43, v3
	v_med3_i32 v38, v38, s43, v3
	v_med3_i32 v42, v42, s43, v3
	v_med3_i32 v50, v50, s43, v3
	v_med3_i32 v54, v54, s43, v3
	v_med3_i32 v58, v58, s43, v3
	v_med3_i32 v62, v62, s43, v3
	v_med3_i32 v64, v66, s43, v3
	v_med3_i32 v65, v70, s43, v3
	v_med3_i32 v66, v74, s43, v3
	v_perm_b32 v29, v29, v17, s44
	v_perm_b32 v61, v68, v61, s44
	v_med3_i32 v34, v34, s43, v3
	v_med3_i32 v46, v46, s43, v3
	v_med3_i32 v68, v14, s43, v3
	v_or3_b32 v14, v15, v16, v20
	v_or3_b32 v15, v28, v24, v32
	v_or3_b32 v16, v44, v36, v40
	v_or3_b32 v17, v56, v48, v52
	v_and_b32_e32 v20, 0xff00, v21
	v_and_b32_e32 v21, 0xff0000, v25
	v_and_b32_e32 v24, 0xff00, v37
	v_and_b32_e32 v25, 0xff0000, v41
	v_and_b32_e32 v28, 0xff00, v45
	v_and_b32_e32 v32, 0xff0000, v53
	v_and_b32_e32 v36, 0xff00, v57
	v_and_b32_e32 v37, 0xff0000, v60
	v_lshlrev_b32_e32 v22, 8, v22
	v_lshlrev_b32_e32 v26, 16, v26
	v_perm_b32 v18, v30, v18, s44
	v_lshlrev_b32_e32 v30, 8, v38
	v_lshlrev_b32_e32 v38, 16, v42
	v_lshlrev_b32_e32 v40, 8, v54
	v_lshlrev_b32_e32 v41, 16, v58
	v_perm_b32 v42, v62, v50, s44
	v_lshlrev_b32_e32 v44, 8, v65
	v_lshlrev_b32_e32 v45, 16, v66
	v_med3_i32 v19, v19, s43, v3
	v_med3_i32 v23, v23, s43, v3
	v_med3_i32 v27, v27, s43, v3
	v_med3_i32 v31, v31, s43, v3
	v_med3_i32 v35, v35, s43, v3
	v_med3_i32 v39, v39, s43, v3
	v_med3_i32 v43, v43, s43, v3
	v_med3_i32 v47, v47, s43, v3
	v_med3_i32 v48, v51, s43, v3
	v_med3_i32 v50, v55, s43, v3
	v_med3_i32 v51, v59, s43, v3
	v_med3_i32 v54, v71, s43, v3
	v_med3_i32 v55, v75, s43, v3
	v_perm_b32 v34, v46, v34, s44
	v_perm_b32 v46, v68, v64, s44
	v_med3_i32 v52, v63, s43, v3
	v_med3_i32 v53, v67, s43, v3
	v_med3_i32 v56, v78, s43, v3
	global_store_dwordx4 v[10:11], v[14:17], off
	v_and_b32_e32 v10, 0xff00, v22
	v_and_b32_e32 v11, 0xff0000, v26
	v_or3_b32 v14, v29, v20, v21
	v_or3_b32 v15, v33, v24, v25
	v_or3_b32 v16, v49, v28, v32
	v_or3_b32 v17, v61, v36, v37
	v_and_b32_e32 v20, 0xff00, v30
	v_and_b32_e32 v21, 0xff0000, v38
	v_and_b32_e32 v22, 0xff00, v40
	v_and_b32_e32 v24, 0xff0000, v41
	v_and_b32_e32 v25, 0xff00, v44
	v_and_b32_e32 v26, 0xff0000, v45
	v_lshlrev_b32_e32 v23, 8, v23
	v_lshlrev_b32_e32 v27, 16, v27
	v_perm_b32 v19, v31, v19, s44
	v_lshlrev_b32_e32 v28, 8, v39
	v_lshlrev_b32_e32 v29, 16, v43
	v_perm_b32 v30, v47, v35, s44
	v_lshlrev_b32_e32 v31, 8, v50
	v_lshlrev_b32_e32 v32, 16, v51
	v_lshlrev_b32_e32 v35, 8, v54
	v_lshlrev_b32_e32 v36, 16, v55
	v_perm_b32 v33, v52, v48, s44
	v_perm_b32 v37, v56, v53, s44
	global_store_dwordx4 v[8:9], v[14:17], off offset:-4096
	s_nop 1
	v_or3_b32 v14, v18, v10, v11
	v_or3_b32 v15, v34, v20, v21
	v_or3_b32 v16, v42, v22, v24
	v_or3_b32 v17, v46, v25, v26
	v_and_b32_e32 v10, 0xff00, v23
	v_and_b32_e32 v11, 0xff0000, v27
	v_and_b32_e32 v18, 0xff00, v28
	v_and_b32_e32 v20, 0xff0000, v29
	v_and_b32_e32 v21, 0xff00, v31
	v_and_b32_e32 v22, 0xff0000, v32
	v_and_b32_e32 v23, 0xff00, v35
	v_and_b32_e32 v24, 0xff0000, v36
	global_store_dwordx4 v[8:9], v[14:17], off
	v_or3_b32 v8, v19, v10, v11
	v_or3_b32 v9, v30, v18, v20
	v_or3_b32 v10, v33, v21, v22
	v_or3_b32 v11, v37, v23, v24
	global_store_dwordx4 v[12:13], v[8:11], off
	s_cbranch_scc1 .LBB0_1149
